# Proj epilogue fast path in P3 (same scheme as SwiGLU) and M3 xor-shuffle reductions via DPP quad_perm/row_mirror instead of 35 serial ds_bpermute round trips per unit
# speedup vs baseline: 1.0087x; 1.0017x over previous
; __device__ __forceinline__ unsigned cvt_pk_bf16(float lo, float hi) { unsigned r; asm volatile("v_cvt_pk_bf16_f32 %0, %1, %2" : "=v"(r) : "v"(lo), "v"(hi)); return r; }
;     __device__ __forceinline__ void operator()(const f32x4 (&acc)[2][2][4][2], const Unit& u, int wr, int wc, int fr, int fq) const {
;         const int row0 = u.pm * BM + wr * 64 + fr, col0 = u.pn * BM + wc * 32 + 8 * fq; const bool tab = (u.pm == rt_pm);
;         if (u.pn < gate_tile) {
; #pragma unroll
;             for (int ai = 0; ai < 2; ++ai)
; #pragma unroll
;                 for (int m = 0; m < 4; ++m) {
;                     const int row = row0 + ai * HALF + m * 16; const float r = tab ? rtab[row - u.pm * BM] : row_rstd(ss, row);
; #pragma unroll
;                     for (int bj = 0; bj < 2; ++bj) {
;                         const f32x4 v0 = acc[ai][bj][m][0] * r, v1 = acc[ai][bj][m][1] * r;
;                         u32x4 w; w.x = cvt_pk_bf16(v0[0], v0[1]); w.y = cvt_pk_bf16(v0[2], v0[3]); w.z = cvt_pk_bf16(v1[0], v1[1]); w.w = cvt_pk_bf16(v1[2], v1[3]);
;                         *(u32x4*)(P + (size_t)row * ldp + col0 + bj * HALF) = w;
;                     }
.LBB0_505:
	s_cmp_eq_u64 s[30:31], 0
	s_cbranch_scc0 .Lslow_p3
	ds_read_b32 v202, v147
	ds_read_b32 v203, v147 offset:64
	ds_read_b32 v204, v147 offset:128
	ds_read_b32 v205, v147 offset:192
	ds_read_b32 v206, v147 offset:512
	ds_read_b32 v207, v147 offset:576
	ds_read_b32 v208, v147 offset:640
	ds_read_b32 v209, v147 offset:704
	v_lshl_or_b32 v200, s28, 8, v148
	v_mov_b32_e32 v201, 0
	v_lshl_add_u64 v[200:201], v[200:201], 1, s[78:79]
	s_waitcnt lgkmcnt(0)
	v_mov_b32_e32 v130, v202
	v_pk_mul_f32 v[124:125], v[124:125], v[130:131] op_sel_hi:[1,0]
	v_pk_mul_f32 v[132:133], v[122:123], v[130:131] op_sel_hi:[1,0]
	v_pk_mul_f32 v[122:123], v[120:121], v[130:131] op_sel_hi:[1,0]
	v_cvt_pk_bf16_f32 v120, v124, v125
	v_pk_mul_f32 v[126:127], v[126:127], v[130:131] op_sel_hi:[1,0]
	v_mad_u64_u32 v[124:125], s[0:1], v140, s57, v[200:201]
	v_cvt_pk_bf16_f32 v121, v126, v127
	v_cvt_pk_bf16_f32 v122, v122, v123
	v_cvt_pk_bf16_f32 v123, v132, v133
	global_store_dwordx4 v[124:125], v[120:123], off
	s_nop 1
	v_pk_mul_f32 v[118:119], v[118:119], v[130:131] op_sel_hi:[1,0]
	v_pk_mul_f32 v[116:117], v[116:117], v[130:131] op_sel_hi:[1,0]
	v_pk_mul_f32 v[120:121], v[114:115], v[130:131] op_sel_hi:[1,0]
	v_pk_mul_f32 v[114:115], v[112:113], v[130:131] op_sel_hi:[1,0]
	v_cvt_pk_bf16_f32 v112, v116, v117
	v_cvt_pk_bf16_f32 v113, v118, v119
	v_cvt_pk_bf16_f32 v114, v114, v115
	v_cvt_pk_bf16_f32 v115, v120, v121
	global_store_dwordx4 v[124:125], v[112:115], off offset:256
	s_nop 1
	s_nop 0
	v_or_b32_e32 v112, 16, v140
	v_mov_b32_e32 v114, v203
	v_pk_mul_f32 v[108:109], v[108:109], v[114:115] op_sel_hi:[1,0]
	v_pk_mul_f32 v[116:117], v[106:107], v[114:115] op_sel_hi:[1,0]
	v_pk_mul_f32 v[106:107], v[104:105], v[114:115] op_sel_hi:[1,0]
	v_cvt_pk_bf16_f32 v104, v108, v109
	v_pk_mul_f32 v[110:111], v[110:111], v[114:115] op_sel_hi:[1,0]
	v_mad_u64_u32 v[108:109], s[12:13], v112, s57, v[200:201]
	v_cvt_pk_bf16_f32 v105, v110, v111
	v_cvt_pk_bf16_f32 v106, v106, v107
	v_cvt_pk_bf16_f32 v107, v116, v117
	global_store_dwordx4 v[108:109], v[104:107], off
	s_nop 1
	v_pk_mul_f32 v[100:101], v[100:101], v[114:115] op_sel_hi:[1,0]
	v_pk_mul_f32 v[102:103], v[102:103], v[114:115] op_sel_hi:[1,0]
	v_pk_mul_f32 v[104:105], v[98:99], v[114:115] op_sel_hi:[1,0]
	v_pk_mul_f32 v[98:99], v[96:97], v[114:115] op_sel_hi:[1,0]
	v_cvt_pk_bf16_f32 v96, v100, v101
	v_cvt_pk_bf16_f32 v97, v102, v103
	v_cvt_pk_bf16_f32 v98, v98, v99
	v_cvt_pk_bf16_f32 v99, v104, v105
	global_store_dwordx4 v[108:109], v[96:99], off offset:256
	s_nop 1
	s_nop 0
	v_or_b32_e32 v96, 32, v140
	v_mov_b32_e32 v98, v204
	v_pk_mul_f32 v[92:93], v[92:93], v[98:99] op_sel_hi:[1,0]
	v_pk_mul_f32 v[100:101], v[90:91], v[98:99] op_sel_hi:[1,0]
	v_pk_mul_f32 v[90:91], v[88:89], v[98:99] op_sel_hi:[1,0]
	v_cvt_pk_bf16_f32 v88, v92, v93
	v_pk_mul_f32 v[94:95], v[94:95], v[98:99] op_sel_hi:[1,0]
	v_mad_u64_u32 v[92:93], s[12:13], v96, s57, v[200:201]
	v_cvt_pk_bf16_f32 v89, v94, v95
	v_cvt_pk_bf16_f32 v90, v90, v91
	v_cvt_pk_bf16_f32 v91, v100, v101
	global_store_dwordx4 v[92:93], v[88:91], off
	s_nop 1
	v_pk_mul_f32 v[84:85], v[84:85], v[98:99] op_sel_hi:[1,0]
	v_pk_mul_f32 v[86:87], v[86:87], v[98:99] op_sel_hi:[1,0]
	v_pk_mul_f32 v[88:89], v[82:83], v[98:99] op_sel_hi:[1,0]
	v_pk_mul_f32 v[82:83], v[80:81], v[98:99] op_sel_hi:[1,0]
	v_cvt_pk_bf16_f32 v80, v84, v85
	v_cvt_pk_bf16_f32 v81, v86, v87
	v_cvt_pk_bf16_f32 v82, v82, v83
	v_cvt_pk_bf16_f32 v83, v88, v89
	global_store_dwordx4 v[92:93], v[80:83], off offset:256
	s_nop 1
	s_nop 0
	v_or_b32_e32 v80, 48, v140
	v_mov_b32_e32 v82, v205
	v_pk_mul_f32 v[76:77], v[76:77], v[82:83] op_sel_hi:[1,0]
	v_pk_mul_f32 v[84:85], v[74:75], v[82:83] op_sel_hi:[1,0]
	v_pk_mul_f32 v[74:75], v[72:73], v[82:83] op_sel_hi:[1,0]
	v_cvt_pk_bf16_f32 v72, v76, v77
	v_pk_mul_f32 v[78:79], v[78:79], v[82:83] op_sel_hi:[1,0]
	v_mad_u64_u32 v[76:77], s[12:13], v80, s57, v[200:201]
	v_cvt_pk_bf16_f32 v73, v78, v79
	v_cvt_pk_bf16_f32 v74, v74, v75
	v_cvt_pk_bf16_f32 v75, v84, v85
	global_store_dwordx4 v[76:77], v[72:75], off
	s_nop 1
	v_pk_mul_f32 v[68:69], v[68:69], v[82:83] op_sel_hi:[1,0]
	v_pk_mul_f32 v[70:71], v[70:71], v[82:83] op_sel_hi:[1,0]
; __device__ __forceinline__ unsigned cvt_pk_bf16(float lo, float hi) { unsigned r; asm volatile("v_cvt_pk_bf16_f32 %0, %1, %2" : "=v"(r) : "v"(lo), "v"(hi)); return r; }
;     __device__ __forceinline__ void operator()(const f32x4 (&acc)[2][2][4][2], const Unit& u, int wr, int wc, int fr, int fq) const {
;         const int row0 = u.pm * BM + wr * 64 + fr, col0 = u.pn * BM + wc * 32 + 8 * fq; const bool tab = (u.pm == rt_pm);
;         if (u.pn < gate_tile) {
; #pragma unroll
;             for (int ai = 0; ai < 2; ++ai)
; #pragma unroll
;                 for (int m = 0; m < 4; ++m) {
;                     const int row = row0 + ai * HALF + m * 16; const float r = tab ? rtab[row - u.pm * BM] : row_rstd(ss, row);
; #pragma unroll
;                     for (int bj = 0; bj < 2; ++bj) {
;                         const f32x4 v0 = acc[ai][bj][m][0] * r, v1 = acc[ai][bj][m][1] * r;
;                         u32x4 w; w.x = cvt_pk_bf16(v0[0], v0[1]); w.y = cvt_pk_bf16(v0[2], v0[3]); w.z = cvt_pk_bf16(v1[0], v1[1]); w.w = cvt_pk_bf16(v1[2], v1[3]);
;                         *(u32x4*)(P + (size_t)row * ldp + col0 + bj * HALF) = w;
;                     }
	v_pk_mul_f32 v[72:73], v[66:67], v[82:83] op_sel_hi:[1,0]
	v_pk_mul_f32 v[66:67], v[64:65], v[82:83] op_sel_hi:[1,0]
	v_cvt_pk_bf16_f32 v64, v68, v69
	v_cvt_pk_bf16_f32 v65, v70, v71
	v_cvt_pk_bf16_f32 v66, v66, v67
	v_cvt_pk_bf16_f32 v67, v72, v73
	global_store_dwordx4 v[76:77], v[64:67], off offset:256
	s_nop 1
	s_nop 0
	v_add_u32_e32 v64, 0x80, v140
	v_mov_b32_e32 v66, v206
	v_pk_mul_f32 v[60:61], v[60:61], v[66:67] op_sel_hi:[1,0]
	v_pk_mul_f32 v[68:69], v[58:59], v[66:67] op_sel_hi:[1,0]
	v_pk_mul_f32 v[58:59], v[56:57], v[66:67] op_sel_hi:[1,0]
	v_cvt_pk_bf16_f32 v56, v60, v61
	v_pk_mul_f32 v[62:63], v[62:63], v[66:67] op_sel_hi:[1,0]
	v_mad_u64_u32 v[60:61], s[12:13], v64, s57, v[200:201]
	v_cvt_pk_bf16_f32 v57, v62, v63
	v_cvt_pk_bf16_f32 v58, v58, v59
	v_cvt_pk_bf16_f32 v59, v68, v69
	global_store_dwordx4 v[60:61], v[56:59], off
	s_nop 1
	v_pk_mul_f32 v[52:53], v[52:53], v[66:67] op_sel_hi:[1,0]
	v_pk_mul_f32 v[54:55], v[54:55], v[66:67] op_sel_hi:[1,0]
	v_pk_mul_f32 v[56:57], v[50:51], v[66:67] op_sel_hi:[1,0]
	v_pk_mul_f32 v[50:51], v[48:49], v[66:67] op_sel_hi:[1,0]
	v_cvt_pk_bf16_f32 v48, v52, v53
	v_cvt_pk_bf16_f32 v49, v54, v55
	v_cvt_pk_bf16_f32 v50, v50, v51
	v_cvt_pk_bf16_f32 v51, v56, v57
	global_store_dwordx4 v[60:61], v[48:51], off offset:256
	s_nop 1
	s_nop 0
	v_add_u32_e32 v48, 0x90, v140
	v_mov_b32_e32 v50, v207
	v_pk_mul_f32 v[44:45], v[44:45], v[50:51] op_sel_hi:[1,0]
	v_pk_mul_f32 v[52:53], v[42:43], v[50:51] op_sel_hi:[1,0]
	v_pk_mul_f32 v[42:43], v[40:41], v[50:51] op_sel_hi:[1,0]
	v_cvt_pk_bf16_f32 v40, v44, v45
	v_pk_mul_f32 v[46:47], v[46:47], v[50:51] op_sel_hi:[1,0]
	v_mad_u64_u32 v[44:45], s[12:13], v48, s57, v[200:201]
	v_cvt_pk_bf16_f32 v41, v46, v47
	v_cvt_pk_bf16_f32 v42, v42, v43
	v_cvt_pk_bf16_f32 v43, v52, v53
	global_store_dwordx4 v[44:45], v[40:43], off
	s_nop 1
	v_pk_mul_f32 v[36:37], v[36:37], v[50:51] op_sel_hi:[1,0]
	v_pk_mul_f32 v[38:39], v[38:39], v[50:51] op_sel_hi:[1,0]
	v_pk_mul_f32 v[40:41], v[34:35], v[50:51] op_sel_hi:[1,0]
	v_pk_mul_f32 v[34:35], v[32:33], v[50:51] op_sel_hi:[1,0]
	v_cvt_pk_bf16_f32 v32, v36, v37
	v_cvt_pk_bf16_f32 v33, v38, v39
	v_cvt_pk_bf16_f32 v34, v34, v35
	v_cvt_pk_bf16_f32 v35, v40, v41
	global_store_dwordx4 v[44:45], v[32:35], off offset:256
	s_nop 1
	s_nop 0
	v_add_u32_e32 v32, 0xa0, v140
	v_mov_b32_e32 v34, v208
	v_pk_mul_f32 v[28:29], v[28:29], v[34:35] op_sel_hi:[1,0]
	v_pk_mul_f32 v[36:37], v[26:27], v[34:35] op_sel_hi:[1,0]
	v_pk_mul_f32 v[26:27], v[24:25], v[34:35] op_sel_hi:[1,0]
	v_cvt_pk_bf16_f32 v24, v28, v29
	v_pk_mul_f32 v[30:31], v[30:31], v[34:35] op_sel_hi:[1,0]
	v_mad_u64_u32 v[28:29], s[12:13], v32, s57, v[200:201]
	v_cvt_pk_bf16_f32 v25, v30, v31
	v_cvt_pk_bf16_f32 v26, v26, v27
	v_cvt_pk_bf16_f32 v27, v36, v37
	global_store_dwordx4 v[28:29], v[24:27], off
	s_nop 1
	v_pk_mul_f32 v[20:21], v[20:21], v[34:35] op_sel_hi:[1,0]
	v_pk_mul_f32 v[22:23], v[22:23], v[34:35] op_sel_hi:[1,0]
	v_pk_mul_f32 v[24:25], v[18:19], v[34:35] op_sel_hi:[1,0]
	v_pk_mul_f32 v[18:19], v[16:17], v[34:35] op_sel_hi:[1,0]
	v_cvt_pk_bf16_f32 v16, v20, v21
	v_cvt_pk_bf16_f32 v17, v22, v23
	v_cvt_pk_bf16_f32 v18, v18, v19
	v_cvt_pk_bf16_f32 v19, v24, v25
	global_store_dwordx4 v[28:29], v[16:19], off offset:256
	s_nop 1
	s_nop 0
	v_add_u32_e32 v16, 0xb0, v140
	v_mov_b32_e32 v18, v209
	v_pk_mul_f32 v[12:13], v[12:13], v[18:19] op_sel_hi:[1,0]
	v_pk_mul_f32 v[20:21], v[10:11], v[18:19] op_sel_hi:[1,0]
	v_pk_mul_f32 v[10:11], v[8:9], v[18:19] op_sel_hi:[1,0]
	v_cvt_pk_bf16_f32 v8, v12, v13
	v_pk_mul_f32 v[14:15], v[14:15], v[18:19] op_sel_hi:[1,0]
	v_mad_u64_u32 v[12:13], s[0:1], v16, s57, v[200:201]
	v_cvt_pk_bf16_f32 v9, v14, v15
	v_cvt_pk_bf16_f32 v10, v10, v11
	v_cvt_pk_bf16_f32 v11, v20, v21
	global_store_dwordx4 v[12:13], v[8:11], off
	s_nop 1
	v_pk_mul_f32 v[6:7], v[6:7], v[18:19] op_sel_hi:[1,0]
	v_pk_mul_f32 v[4:5], v[4:5], v[18:19] op_sel_hi:[1,0]
	v_pk_mul_f32 v[8:9], v[2:3], v[18:19] op_sel_hi:[1,0]
	v_pk_mul_f32 v[2:3], v[0:1], v[18:19] op_sel_hi:[1,0]
	v_cvt_pk_bf16_f32 v0, v4, v5
	v_cvt_pk_bf16_f32 v1, v6, v7
	s_nop 0
	v_cvt_pk_bf16_f32 v2, v2, v3
	v_cvt_pk_bf16_f32 v3, v8, v9
	global_store_dwordx4 v[12:13], v[0:3], off offset:256
	s_nop 1
	s_branch .Ljoin_p3

; __device__ __forceinline__ unsigned cvt_pk_bf16(float lo, float hi) { unsigned r; asm volatile("v_cvt_pk_bf16_f32 %0, %1, %2" : "=v"(r) : "v"(lo), "v"(hi)); return r; }
;     __device__ __forceinline__ void operator()(const f32x4 (&acc)[2][2][4][2], const Unit& u, int wr, int wc, int fr, int fq) const {
;     ...
;                     const int row = row0 + ai * HALF + m * 16; const float r = tab ? rtab[row - u.pm * BM] : row_rstd(ss, row);
; #pragma unroll
;                     for (int bj = 0; bj < 2; ++bj) {
;                         const f32x4 v0 = acc[ai][bj][m][0] * r, v1 = acc[ai][bj][m][1] * r;
;                         u32x4 w; w.x = cvt_pk_bf16(v0[0], v0[1]); w.y = cvt_pk_bf16(v0[2], v0[3]); w.z = cvt_pk_bf16(v1[0], v1[1]); w.w = cvt_pk_bf16(v1[2], v1[3]);
;                         *(u32x4*)(P + (size_t)row * ldp + col0 + bj * HALF) = w;
;                     }
.LBB0_537:
	s_waitcnt lgkmcnt(0)
	v_pk_mul_f32 v[12:13], v[12:13], v[18:19] op_sel_hi:[1,0]
	v_pk_mul_f32 v[20:21], v[10:11], v[18:19] op_sel_hi:[1,0]
	v_pk_mul_f32 v[10:11], v[8:9], v[18:19] op_sel_hi:[1,0]
	v_cvt_pk_bf16_f32 v8, v12, v13
	v_mov_b64_e32 v[12:13], s[78:79]
	v_pk_mul_f32 v[14:15], v[14:15], v[18:19] op_sel_hi:[1,0]
	v_mad_u64_u32 v[12:13], s[0:1], v16, s57, v[12:13]
	v_cvt_pk_bf16_f32 v9, v14, v15
	v_mov_b32_e32 v14, v13
	v_mad_u64_u32 v[14:15], s[0:1], v17, s57, v[14:15]
	v_mov_b32_e32 v13, v14
	v_lshl_add_u64 v[12:13], v[128:129], 1, v[12:13]
	v_cvt_pk_bf16_f32 v10, v10, v11
	v_cvt_pk_bf16_f32 v11, v20, v21
	global_store_dwordx4 v[12:13], v[8:11], off
	v_pk_mul_f32 v[6:7], v[6:7], v[18:19] op_sel_hi:[1,0]
	v_pk_mul_f32 v[4:5], v[4:5], v[18:19] op_sel_hi:[1,0]
	v_pk_mul_f32 v[8:9], v[2:3], v[18:19] op_sel_hi:[1,0]
	v_pk_mul_f32 v[2:3], v[0:1], v[18:19] op_sel_hi:[1,0]
	v_cvt_pk_bf16_f32 v0, v4, v5
	v_cvt_pk_bf16_f32 v1, v6, v7
	s_nop 0
	v_cvt_pk_bf16_f32 v2, v2, v3
	v_cvt_pk_bf16_f32 v3, v8, v9
	global_store_dwordx4 v[12:13], v[0:3], off offset:256
.Ljoin_p3:
	s_andn2_b64 vcc, exec, s[10:11]
	s_mov_b64 s[0:1], -1
	s_cbranch_vccnz .LBB0_460
.LBB0_538:
	s_andn2_b64 vcc, exec, s[4:5]
	s_cbranch_vccnz .LBB0_459
	s_barrier
	s_branch .LBB0_459

; __device__ __forceinline__ void m3_phase(const Params& p, unsigned char* ldsg, int G) {
;     ...
;     if ((int)blockIdx.x < NCH * NH) M3_ISSUE((int)blockIdx.x);
;     for (int u = blockIdx.x; u < NCH * NH; u += G) {
;         const int c = u >> 2, h = u & 3, t0 = c * CL;
;         {
;             const int r = tid >> 4, cgp = tid & 15;
;             if (wave == 0) {
;                 const float b = wave_incl_sum(log_sigmoid_f(g_fp), lane);
;                 const float uu = g_ig - b;
;                 const float U = wave_incl_max(uu, lane);
;                 const float mp = g_mp;
;                 const float M = fmaxf(mp, U);
;                 sU[lane] = uu; sM[lane] = M; sIW[lane] = expf(mp - M); sEMT[lane] = expf(-(b + M)); sRS[lane] = 0.f; sHS[lane] = 0.f;
;             } else if (wave == 1) {
;                 sN[lane] = g_n0; sN[lane + 64] = g_n1;
;             }
; #pragma unroll
;             for (int pass = 0; pass < 2; ++pass) { const int l = r + 32 * pass;
;                 *(u32x4*)(Qs + l * QP + cgp * 8) = gq[pass]; *(u32x4*)(Ks + l * QP + cgp * 8) = gk[pass]; *(u32x4*)(Os + l * QP + cgp * 8) = go[pass];
; #pragma unroll
;                 for (int e = 0; e < 8; ++e) VT[tsw(cgp * 8 + e, l)] = (bf16)(gv[pass][e >> 1] >> ((e & 1) * 16)); }
; #pragma unroll
;             for (int i = 0; i < 4; ++i) { const int idx = tid + 512 * i, vd = idx >> 4, kc = (idx & 15) * 8; *(u32x4*)(CTs + vd * QP + kc) = gc[i]; }
;             { const int un = (u + G < NCH * NH) ? u + G : u; M3_ISSUE(un); }
;         }
;         LBAR();
;         {
;             const int l = tid >> 3, part = tid & 7; float s = 0.f;
;             float qa[8], qb[8]; unpack8(*(const u32x4*)(Qs + l * QP + part * 16), qa); unpack8(*(const u32x4*)(Qs + l * QP + part * 16 + 8), qb);
;             const f32x4 n0 = *(const f32x4*)(sN + part * 16), n1 = *(const f32x4*)(sN + part * 16 + 4), n2 = *(const f32x4*)(sN + part * 16 + 8), n3 = *(const f32x4*)(sN + part * 16 + 12);
;             s = ((qa[0] * n0[0] + qa[1] * n0[1]) + (qa[2] * n0[2] + qa[3] * n0[3])) + ((qa[4] * n1[0] + qa[5] * n1[1]) + (qa[6] * n1[2] + qa[7] * n1[3]))
;               + ((qb[0] * n2[0] + qb[1] * n2[1]) + (qb[2] * n2[2] + qb[3] * n2[3])) + ((qb[4] * n3[0] + qb[5] * n3[1]) + (qb[6] * n3[2] + qb[7] * n3[3]));
;             s += __shfl_xor(s, 1); s += __shfl_xor(s, 2); s += __shfl_xor(s, 4);
.LBB0_1125:
	s_add_i32 s83, s42, s74
	s_cmpk_gt_i32 s83, 0x3ff
	s_cselect_b64 s[44:45], -1, 0
	s_cmpk_lt_i32 s83, 0x400
	s_cselect_b32 s42, s83, s42
	s_ashr_i32 s84, s42, 2
	s_lshl_b32 s87, s84, 6
	s_waitcnt vmcnt(16)
	ds_write_b128 v105, v[8:11]
	s_waitcnt vmcnt(15)
	ds_write_b128 v105, v[0:3] offset:17408
	s_waitcnt vmcnt(13)
	ds_write_b128 v106, v[12:15]
	ds_write_b16 v171, v4 offset:34816
	ds_write_b16_d16_hi v171, v4 offset:34960
	ds_write_b16 v171, v5 offset:35104
	ds_write_b16_d16_hi v171, v5 offset:35248
	ds_write_b16 v171, v6 offset:35392
	ds_write_b16_d16_hi v171, v6 offset:35536
	ds_write_b16 v171, v7 offset:35680
	ds_write_b16_d16_hi v171, v7 offset:35824
	s_waitcnt vmcnt(12)
	ds_write_b128 v105, v[24:27] offset:8704
	s_waitcnt vmcnt(11)
	ds_write_b128 v105, v[20:23] offset:26112
	s_waitcnt vmcnt(9)
	ds_write_b128 v108, v[28:31]
	ds_write_b16 v174, v16 offset:34816
	ds_write_b16_d16_hi v174, v16 offset:34960
	ds_write_b16 v174, v17 offset:35104
	ds_write_b16_d16_hi v174, v17 offset:35248
	ds_write_b16 v174, v18 offset:35392
	ds_write_b16_d16_hi v174, v18 offset:35536
	ds_write_b16 v174, v19 offset:35680
	ds_write_b16_d16_hi v174, v19 offset:35824
	s_waitcnt vmcnt(8)
	ds_write_b128 v109, v[32:35]
	s_waitcnt vmcnt(7)
	ds_write_b128 v175, v[36:39] offset:53248
	s_waitcnt vmcnt(6)
	ds_write_b128 v109, v[40:43] offset:17408
	s_waitcnt vmcnt(5)
	ds_write_b128 v176, v[44:47] offset:53248
	v_or_b32_e32 v16, s87, v165
	v_ashrrev_i32_e32 v17, 31, v16
	v_mov_b64_e32 v[18:19], s[78:79]
	v_lshlrev_b64 v[0:1], 11, v[16:17]
	v_mad_i64_i32 v[4:5], s[46:47], v16, s80, v[18:19]
	v_add_u32_e32 v16, 32, v16
	v_ashrrev_i32_e32 v17, 31, v16
	s_and_b32 s85, s42, 3
	v_lshlrev_b64 v[20:21], 11, v[16:17]
	v_lshl_add_u64 v[0:1], s[56:57], 0, v[0:1]
	s_lshl_b32 s42, s85, 8
	v_lshl_add_u64 v[20:21], s[56:57], 0, v[20:21]
	v_mad_i64_i32 v[16:17], s[46:47], v16, s80, v[18:19]
	v_lshl_add_u64 v[0:1], v[0:1], 0, s[42:43]
	v_lshl_add_u64 v[4:5], v[4:5], 0, s[42:43]
	v_lshl_add_u64 v[20:21], v[20:21], 0, s[42:43]
	v_lshl_add_u64 v[16:17], v[16:17], 0, s[42:43]
	s_lshl_b32 s42, s85, 14
	s_add_i32 s46, s42, s84
	s_lshl_b32 s42, s85, 2
	s_mulk_i32 s85, 0xc100
	v_add_u32_e32 v32, s46, v110
	v_add_u32_e32 v34, s46, v112
	v_add_u32_e32 v40, s46, v113
	v_add_u32_e32 v42, s46, v114
	v_or_b32_e32 v48, s87, v153
	s_add_i32 s46, s46, s85
	v_ashrrev_i32_e32 v49, 31, v48
	s_ashr_i32 s47, s46, 31
	v_ashrrev_i32_e32 v33, 31, v32
	v_ashrrev_i32_e32 v35, 31, v34
	v_ashrrev_i32_e32 v41, 31, v40
	v_ashrrev_i32_e32 v43, 31, v42
	v_lshlrev_b64 v[48:49], 5, v[48:49]
	s_lshl_b64 s[84:85], s[46:47], 2
	v_lshlrev_b64 v[32:33], 9, v[32:33]
	v_lshlrev_b64 v[34:35], 9, v[34:35]
	v_lshlrev_b64 v[40:41], 9, v[40:41]
	v_lshlrev_b64 v[42:43], 9, v[42:43]
	v_lshl_add_u64 v[48:49], s[54:55], 0, v[48:49]
	s_add_u32 s84, s0, s84
	v_lshl_add_u64 v[0:1], v[0:1], 0, v[80:81]
	v_lshl_add_u64 v[12:13], v[4:5], 0, v[80:81]
	v_lshl_add_u64 v[20:21], v[20:21], 0, v[80:81]
	v_lshl_add_u64 v[28:29], v[16:17], 0, v[80:81]
	v_lshl_add_u64 v[32:33], v[82:83], 0, v[32:33]
	v_lshl_add_u64 v[36:37], v[82:83], 0, v[34:35]
	v_lshl_add_u64 v[40:41], v[82:83], 0, v[40:41]
	v_lshl_add_u64 v[44:45], v[82:83], 0, v[42:43]
	v_lshl_add_u64 v[48:49], v[48:49], 0, s[42:43]
	s_addc_u32 s85, s1, s85
	s_lshl_b64 s[46:47], s[46:47], 9
	global_load_dwordx4 v[8:11], v[0:1], off
	s_nop 0
	global_load_dwordx4 v[0:3], v[0:1], off offset:1024
	s_nop 0
	global_load_dwordx4 v[4:7], v[12:13], off offset:2048
	s_nop 0
	global_load_dwordx4 v[12:15], v[12:13], off offset:3072
	s_nop 0
	global_load_dwordx4 v[24:27], v[20:21], off
	s_nop 0
	global_load_dwordx4 v[20:23], v[20:21], off offset:1024
	s_nop 0
	global_load_dwordx4 v[16:19], v[28:29], off offset:2048
	s_nop 0
	global_load_dwordx4 v[28:31], v[28:29], off offset:3072
	s_nop 0
	global_load_dwordx4 v[32:35], v[32:33], off
	s_nop 0
	global_load_dwordx4 v[36:39], v[36:37], off
	s_nop 0
	global_load_dwordx4 v[40:43], v[40:41], off
	s_nop 0
	global_load_dwordx4 v[44:47], v[44:45], off
	v_lshl_add_u64 v[50:51], v[84:85], 0, s[46:47]
	global_load_dword v130, v[48:49], off
	global_load_dword v193, v[48:49], off offset:16
	global_load_dword v111, v81, s[84:85]
	global_load_dword v195, v[50:51], off
	global_load_dword v194, v[50:51], off offset:256
	s_waitcnt lgkmcnt(0)
	s_barrier
	ds_read_b128 v[48:51], v98
	ds_read_b128 v[52:55], v98 offset:16
	s_waitcnt lgkmcnt(1)
	v_lshlrev_b32_e32 v64, 16, v48
	v_and_b32_e32 v65, 0xffff0000, v48
	v_lshlrev_b32_e32 v66, 16, v49
	v_and_b32_e32 v67, 0xffff0000, v49
	v_lshlrev_b32_e32 v68, 16, v50
	v_and_b32_e32 v69, 0xffff0000, v50
	v_lshlrev_b32_e32 v70, 16, v51
	v_and_b32_e32 v71, 0xffff0000, v51
	ds_read_b128 v[48:51], v99
	s_waitcnt lgkmcnt(1)
	v_lshlrev_b32_e32 v72, 16, v52
	v_and_b32_e32 v73, 0xffff0000, v52
	v_lshlrev_b32_e32 v74, 16, v53
	v_and_b32_e32 v75, 0xffff0000, v53
	v_lshlrev_b32_e32 v76, 16, v54
	v_and_b32_e32 v77, 0xffff0000, v54
	v_lshlrev_b32_e32 v78, 16, v55
	v_and_b32_e32 v79, 0xffff0000, v55
	ds_read_b128 v[52:55], v99 offset:16
	ds_read_b128 v[56:59], v99 offset:32
	ds_read_b128 v[60:63], v99 offset:48
	s_waitcnt lgkmcnt(3)
	v_mul_f32_e32 v49, v49, v65
	v_fmac_f32_e32 v49, v48, v64
	v_mul_f32_e32 v48, v51, v67
	v_fmac_f32_e32 v48, v50, v66
	v_add_f32_e32 v48, v49, v48
	s_waitcnt lgkmcnt(2)
	v_mul_f32_e32 v49, v53, v69
	v_mul_f32_e32 v50, v55, v71
	v_fmac_f32_e32 v49, v52, v68
	v_fmac_f32_e32 v50, v54, v70
	v_add_f32_e32 v49, v49, v50
	v_add_f32_e32 v48, v48, v49
	s_waitcnt lgkmcnt(1)
	v_mul_f32_e32 v49, v57, v73
	v_mul_f32_e32 v50, v59, v75
	v_fmac_f32_e32 v49, v56, v72
	v_fmac_f32_e32 v50, v58, v74
	v_add_f32_e32 v49, v49, v50
	v_add_f32_e32 v48, v48, v49
	s_waitcnt lgkmcnt(0)
	v_mul_f32_e32 v49, v61, v77
	v_mul_f32_e32 v50, v63, v79
	v_fmac_f32_e32 v49, v60, v76
	v_fmac_f32_e32 v50, v62, v78
	v_add_f32_e32 v49, v49, v50
	v_and_b32_e32 v50, 64, v191
	v_add_f32_e32 v48, v48, v49
	v_xor_b32_e32 v49, 1, v191
	v_add_u32_e32 v69, 64, v50
	v_cmp_lt_i32_e32 vcc, v49, v69
	s_nop 1
	v_cndmask_b32_e32 v49, v191, v49, vcc
	v_lshlrev_b32_e32 v196, 2, v49
	s_waitcnt lgkmcnt(0)
	s_nop 1
	v_add_f32_dpp v48, v48, v48 quad_perm:[1,0,3,2] row_mask:0xf bank_mask:0xf
	v_xor_b32_e32 v49, 2, v191
	v_cmp_lt_i32_e32 vcc, v49, v69
	s_nop 1
	v_cndmask_b32_e32 v49, v191, v49, vcc
	v_lshlrev_b32_e32 v197, 2, v49
	s_waitcnt lgkmcnt(0)
	s_nop 1
	v_add_f32_dpp v48, v48, v48 quad_perm:[2,3,0,1] row_mask:0xf bank_mask:0xf
	v_xor_b32_e32 v49, 4, v191
	v_cmp_lt_i32_e32 vcc, v49, v69
	s_nop 1
	v_cndmask_b32_e32 v49, v191, v49, vcc
	v_lshlrev_b32_e32 v198, 2, v49
	s_nop 1
	v_add_f32_dpp v49, v48, v48 row_half_mirror row_mask:0xf bank_mask:0xf
	s_and_saveexec_b64 s[46:47], s[20:21]
	s_cbranch_execz .LBB0_1127
	s_waitcnt lgkmcnt(0)
	v_mov_b32_e32 v48, v49
	ds_write_b32 v100, v48

; __device__ __forceinline__ unsigned f2bf(float f) { unsigned u = __builtin_bit_cast(unsigned, f); return (u + 0x7fffu + ((u >> 16) & 1u)) >> 16; }
; #define LBAR() do { asm volatile("s_waitcnt lgkmcnt(0)" ::: "memory"); __builtin_amdgcn_s_barrier(); asm volatile("" ::: "memory"); } while (0)
; __device__ __forceinline__ void m3_phase(const Params& p, unsigned char* ldsg, int G) {
;     ...
;                 const int s = 16 * st + fr; const float us = sU[s];
; #pragma unroll
;                 for (int j = 0; j < 4; ++j) { const int l = 16 * lt + fq * 4 + j; const float val = (s <= l) ? acc[j] * __expf(us - sM[l]) : 0.f; Ps[l * TP + s] = (bf16)f2bf(val); rs[j] += val; }
;             }
; #pragma unroll
;             for (int j = 0; j < 4; ++j) { float v = rs[j]; v += __shfl_xor(v, 1); v += __shfl_xor(v, 2); v += __shfl_xor(v, 4); v += __shfl_xor(v, 8); if (fr == 0) atomicAdd(&sRS[16 * lt + fq * 4 + j], v); }
;         }
;         LBAR();
;         {
;             f32x4 a1[4], a2[4];
; #pragma unroll
;             for (int n = 0; n < 4; ++n) { a1[n] = (f32x4){0.f, 0.f, 0.f, 0.f}; a2[n] = (f32x4){0.f, 0.f, 0.f, 0.f}; }
; #pragma unroll
;             for (int ks = 0; ks < 2; ++ks) { const bf16x8 a = *(const bf16x8*)(Ps + (16 * lt + fr) * TP + ks * 32 + fq * 8);
; #pragma unroll
;                 for (int n = 0; n < 4; ++n) { const int nt = 4 * (wave & 1) + n; const bf16x8 b = *(const bf16x8*)(VT + tsw(16 * nt + fr, ks * 32 + fq * 8)); a1[n] = __builtin_amdgcn_mfma_f32_16x16x32_bf16(a, b, a1[n], 0, 0, 0); } }
; #pragma unroll
;             for (int ks = 0; ks < 4; ++ks) { const bf16x8 a = *(const bf16x8*)(Qs + (16 * lt + fr) * QP + ks * 32 + fq * 8);
; #pragma unroll
;                 for (int n = 0; n < 4; ++n) { const int nt = 4 * (wave & 1) + n; const bf16x8 b = *(const bf16x8*)(CTs + (16 * nt + fr) * QP + ks * 32 + fq * 8); a2[n] = __builtin_amdgcn_mfma_f32_16x16x32_bf16(a, b, a2[n], 0, 0, 0); } }
; #pragma unroll
;             for (int j = 0; j < 4; ++j) {
;                 const int l = 16 * lt + fq * 4 + j; const float iw = sIW[l]; const float qn = sRS[l] + iw * sQN[l];
;                 const float den = fmaxf(fabsf(qn), sEMT[l]); const float inv = __builtin_amdgcn_rcpf(den); float hs = 0.f;
.LBB0_1143:
	s_or_b64 exec, exec, s[46:47]
	v_bfe_u32 v51, v49, 16, 1
	v_add3_u32 v51, v49, v51, s82
	ds_write_b16_d16_hi v129, v51
	v_xor_b32_e32 v51, 8, v191
	v_add_f32_e32 v50, 0, v70
	v_cmp_lt_i32_e32 vcc, v51, v69
	v_add_f32_e32 v50, v50, v66
	s_nop 0
	v_cndmask_b32_e32 v51, v191, v51, vcc
	v_lshlrev_b32_e32 v199, 2, v51
	s_waitcnt lgkmcnt(0)
	s_nop 1
	v_add_f32_dpp v50, v50, v50 quad_perm:[1,0,3,2] row_mask:0xf bank_mask:0xf
	s_waitcnt lgkmcnt(0)
	s_nop 1
	v_add_f32_dpp v50, v50, v50 quad_perm:[2,3,0,1] row_mask:0xf bank_mask:0xf
	s_waitcnt lgkmcnt(0)
	s_nop 1
	v_add_f32_dpp v51, v50, v50 row_half_mirror row_mask:0xf bank_mask:0xf
	s_nop 1
	v_add_f32_dpp v53, v51, v51 row_mirror row_mask:0xf bank_mask:0xf
	v_add_u32_e32 v50, s2, v102
	s_and_saveexec_b64 s[46:47], s[22:23]
	s_cbranch_execz .LBB0_1145
	s_waitcnt lgkmcnt(0)
	v_mov_b32_e32 v51, v53
	ds_add_f32 v50, v51
.LBB0_1145:
	s_or_b64 exec, exec, s[46:47]
	v_add_f32_e32 v51, 0, v64
	v_add_f32_e32 v51, v51, v52
	s_waitcnt lgkmcnt(0)
	s_nop 1
	v_add_f32_dpp v51, v51, v51 quad_perm:[1,0,3,2] row_mask:0xf bank_mask:0xf
	s_waitcnt lgkmcnt(0)
	s_nop 1
	v_add_f32_dpp v51, v51, v51 quad_perm:[2,3,0,1] row_mask:0xf bank_mask:0xf
	s_waitcnt lgkmcnt(0)
	s_nop 1
	v_add_f32_dpp v51, v51, v51 row_half_mirror row_mask:0xf bank_mask:0xf
	s_nop 1
	v_add_f32_dpp v52, v51, v51 row_mirror row_mask:0xf bank_mask:0xf
	s_and_saveexec_b64 s[46:47], s[22:23]
	s_cbranch_execz .LBB0_1147
	s_waitcnt lgkmcnt(0)
	v_mov_b32_e32 v51, v52
	ds_add_f32 v50, v51 offset:4
.LBB0_1147:
	s_or_b64 exec, exec, s[46:47]
	v_add_f32_e32 v51, 0, v68
	v_add_f32_e32 v48, v51, v48
	s_waitcnt lgkmcnt(0)
	s_nop 1
	v_add_f32_dpp v48, v48, v48 quad_perm:[1,0,3,2] row_mask:0xf bank_mask:0xf
	s_waitcnt lgkmcnt(0)
	s_nop 1
	v_add_f32_dpp v48, v48, v48 quad_perm:[2,3,0,1] row_mask:0xf bank_mask:0xf
	s_waitcnt lgkmcnt(0)
	s_nop 1
	v_add_f32_dpp v48, v48, v48 row_half_mirror row_mask:0xf bank_mask:0xf
	s_nop 1
	v_add_f32_dpp v51, v48, v48 row_mirror row_mask:0xf bank_mask:0xf
	s_and_saveexec_b64 s[46:47], s[22:23]
	s_cbranch_execz .LBB0_1149
	s_waitcnt lgkmcnt(0)
	v_mov_b32_e32 v48, v51
	ds_add_f32 v50, v48 offset:8
.LBB0_1149:
	s_or_b64 exec, exec, s[46:47]
	v_add_f32_e32 v48, 0, v65
	v_add_f32_e32 v48, v48, v49
	s_waitcnt lgkmcnt(0)
	s_nop 1
	v_add_f32_dpp v48, v48, v48 quad_perm:[1,0,3,2] row_mask:0xf bank_mask:0xf
	s_waitcnt lgkmcnt(0)
	s_nop 1
	v_add_f32_dpp v48, v48, v48 quad_perm:[2,3,0,1] row_mask:0xf bank_mask:0xf
	s_waitcnt lgkmcnt(0)
	s_nop 1
	v_add_f32_dpp v48, v48, v48 row_half_mirror row_mask:0xf bank_mask:0xf
	s_nop 1
	v_add_f32_dpp v49, v48, v48 row_mirror row_mask:0xf bank_mask:0xf
	s_and_saveexec_b64 s[46:47], s[22:23]
	s_cbranch_execz .LBB0_1151
	s_waitcnt lgkmcnt(0)
	v_mov_b32_e32 v48, v49
	ds_add_f32 v50, v48 offset:12
.LBB0_1151:
	s_or_b64 exec, exec, s[46:47]
	s_waitcnt lgkmcnt(0)
	s_barrier
	s_waitcnt lgkmcnt(0)
	ds_read_b128 v[48:51], v103
	ds_read_b128 v[52:55], v177 offset:34816
	ds_read_b128 v[56:59], v178 offset:34816
	ds_read_b128 v[64:67], v103 offset:64
	s_waitcnt lgkmcnt(2)
	v_mfma_f32_16x16x32_bf16 v[52:55], v[48:51], v[52:55], 0
	s_waitcnt lgkmcnt(1)
	v_mfma_f32_16x16x32_bf16 v[60:63], v[48:51], v[56:59], 0
	ds_read_b128 v[56:59], v179 offset:34816
	ds_read_b128 v[68:71], v180 offset:34816
	s_waitcnt lgkmcnt(1)
	v_mfma_f32_16x16x32_bf16 v[72:75], v[48:51], v[56:59], 0
	s_waitcnt lgkmcnt(0)
	v_mfma_f32_16x16x32_bf16 v[48:51], v[48:51], v[68:71], 0
	ds_read_b128 v[56:59], v181 offset:34816
	ds_read_b128 v[68:71], v182 offset:34816
	s_waitcnt lgkmcnt(1)
	v_mfma_f32_16x16x32_bf16 v[56:59], v[64:67], v[56:59], v[52:55]
	s_waitcnt lgkmcnt(0)
	v_mfma_f32_16x16x32_bf16 v[60:63], v[64:67], v[68:71], v[60:63]
	s_nop 0
	ds_read_b128 v[52:55], v183 offset:34816
	ds_read_b128 v[68:71], v184 offset:34816
	s_waitcnt lgkmcnt(1)
	v_mfma_f32_16x16x32_bf16 v[52:55], v[64:67], v[52:55], v[72:75]
	s_nop 2
	ds_read_b128 v[72:75], v104
	s_waitcnt lgkmcnt(1)
	v_mfma_f32_16x16x32_bf16 v[48:51], v[64:67], v[68:71], v[48:51]
	ds_read_b128 v[64:67], v185 offset:53248
	ds_read_b128 v[68:71], v104 offset:64
	ds_read_b128 v[76:79], v185 offset:53312
	ds_read_b128 v[200:203], v186 offset:53248
	ds_read_b128 v[204:207], v186 offset:53312
	ds_read_b128 v[208:211], v187 offset:53248
	ds_read_b128 v[212:215], v187 offset:53312
	ds_read_b128 v[216:219], v188 offset:53248
	ds_read_b128 v[220:223], v188 offset:53312
	s_waitcnt lgkmcnt(8)
	v_mfma_f32_16x16x32_bf16 v[64:67], v[72:75], v[64:67], 0
	s_waitcnt lgkmcnt(5)
	v_mfma_f32_16x16x32_bf16 v[200:203], v[72:75], v[200:203], 0
	s_waitcnt lgkmcnt(3)
	v_mfma_f32_16x16x32_bf16 v[208:211], v[72:75], v[208:211], 0
	s_waitcnt lgkmcnt(1)
	v_mfma_f32_16x16x32_bf16 v[72:75], v[72:75], v[216:219], 0
	v_mfma_f32_16x16x32_bf16 v[64:67], v[68:71], v[76:79], v[64:67]
	v_mfma_f32_16x16x32_bf16 v[76:79], v[68:71], v[204:207], v[200:203]
	v_mfma_f32_16x16x32_bf16 v[200:203], v[68:71], v[212:215], v[208:211]
	ds_read_b128 v[204:207], v104 offset:128
	s_nop 1
	ds_read_b128 v[208:211], v185 offset:53376
	s_waitcnt lgkmcnt(2)
	v_mfma_f32_16x16x32_bf16 v[68:71], v[68:71], v[220:223], v[72:75]
	s_nop 2
	ds_read_b128 v[72:75], v186 offset:53376
	ds_read_b128 v[212:215], v104 offset:192
	ds_read_b128 v[216:219], v185 offset:53440
	s_waitcnt lgkmcnt(3)
	v_mfma_f32_16x16x32_bf16 v[64:67], v[204:207], v[208:211], v[64:67]
	ds_read_b128 v[208:211], v186 offset:53440
	ds_read_b128 v[220:223], v187 offset:53376
	ds_read_b128 v[224:227], v187 offset:53440
	s_waitcnt lgkmcnt(5)
	v_mfma_f32_16x16x32_bf16 v[72:75], v[204:207], v[72:75], v[76:79]
	ds_read_b32 v228, v92
	ds_read_b32 v229, v131
	s_nop 0
	ds_read_b32 v76, v132
	ds_read_b32 v238, v133
	s_waitcnt lgkmcnt(1)
; __device__ __forceinline__ unsigned f2bf(float f) { unsigned u = __builtin_bit_cast(unsigned, f); return (u + 0x7fffu + ((u >> 16) & 1u)) >> 16; }
; __device__ __forceinline__ void m3_phase(const Params& p, unsigned char* ldsg, int G) {
;     ...
;             for (int ks = 0; ks < 2; ++ks) { const bf16x8 a = *(const bf16x8*)(Ps + (16 * lt + fr) * TP + ks * 32 + fq * 8);
; #pragma unroll
;                 for (int n = 0; n < 4; ++n) { const int nt = 4 * (wave & 1) + n; const bf16x8 b = *(const bf16x8*)(VT + tsw(16 * nt + fr, ks * 32 + fq * 8)); a1[n] = __builtin_amdgcn_mfma_f32_16x16x32_bf16(a, b, a1[n], 0, 0, 0); } }
; #pragma unroll
;             for (int ks = 0; ks < 4; ++ks) { const bf16x8 a = *(const bf16x8*)(Qs + (16 * lt + fr) * QP + ks * 32 + fq * 8);
; #pragma unroll
;                 for (int n = 0; n < 4; ++n) { const int nt = 4 * (wave & 1) + n; const bf16x8 b = *(const bf16x8*)(CTs + (16 * nt + fr) * QP + ks * 32 + fq * 8); a2[n] = __builtin_amdgcn_mfma_f32_16x16x32_bf16(a, b, a2[n], 0, 0, 0); } }
; #pragma unroll
;             for (int j = 0; j < 4; ++j) {
;                 const int l = 16 * lt + fq * 4 + j; const float iw = sIW[l]; const float qn = sRS[l] + iw * sQN[l];
;                 const float den = fmaxf(fabsf(qn), sEMT[l]); const float inv = __builtin_amdgcn_rcpf(den); float hs = 0.f;
; #pragma unroll
;                 for (int n = 0; n < 4; ++n) { const float v = (a1[n][j] + iw * a2[n][j]) * inv; hs += v * v; Ks[l * QP + 16 * (4 * (wave & 1) + n) + fr] = (bf16)f2bf(v); }
;                 hs += __shfl_xor(hs, 1); hs += __shfl_xor(hs, 2); hs += __shfl_xor(hs, 4); hs += __shfl_xor(hs, 8);
;                 if (fr == 0) atomicAdd(&sHS[l], hs);
	v_fmac_f32_e32 v229, v228, v76
	v_mfma_f32_16x16x32_bf16 v[200:203], v[204:207], v[220:223], v[200:203]
	ds_read_b128 v[220:223], v188 offset:53376
	ds_read_b128 v[246:249], v188 offset:53440
	v_mfma_f32_16x16x32_bf16 v[76:79], v[212:215], v[216:219], v[64:67]
	s_waitcnt lgkmcnt(2)
	s_nop 1
	v_max_f32_e32 v64, v238, v238
	v_max_f32_e64 v64, |v229|, v64
	v_rcp_f32_e32 v216, v64
	v_mfma_f32_16x16x32_bf16 v[64:67], v[212:215], v[208:211], v[72:75]
	s_nop 0
	v_fma_f32 v56, v76, v228, v56
	v_mul_f32_e32 v56, v56, v216
	s_waitcnt lgkmcnt(1)
	v_mfma_f32_16x16x32_bf16 v[72:75], v[204:207], v[220:223], v[68:71]
	v_mfma_f32_16x16x32_bf16 v[68:71], v[212:215], v[224:227], v[200:203]
	s_nop 1
	v_fma_f32 v60, v64, v228, v60
	v_mul_f32_e32 v60, v60, v216
	v_mul_f32_e32 v64, v60, v60
	s_waitcnt lgkmcnt(0)
	v_mfma_f32_16x16x32_bf16 v[72:75], v[212:215], v[246:249], v[72:75]
	v_fmac_f32_e32 v64, v56, v56
	v_fma_f32 v52, v68, v228, v52
	v_mul_f32_e32 v52, v52, v216
	v_fmac_f32_e32 v64, v52, v52
	s_nop 3
	v_fma_f32 v48, v228, v72, v48
	v_mul_f32_e32 v68, v48, v216
	v_fmac_f32_e32 v64, v68, v68
	v_bfe_u32 v72, v56, 16, 1
	v_add3_u32 v56, v56, v72, s82
	v_add_u32_e32 v72, s3, v134
	ds_write_b16_d16_hi v72, v56 offset:17408
	s_waitcnt lgkmcnt(1)
	s_nop 1
	v_add_f32_dpp v48, v64, v64 quad_perm:[1,0,3,2] row_mask:0xf bank_mask:0xf
	v_bfe_u32 v64, v60, 16, 1
	v_add3_u32 v60, v60, v64, s82
	v_add_u32_e32 v64, s33, v134
	ds_write_b16_d16_hi v64, v60 offset:17408
	s_waitcnt lgkmcnt(1)
	s_nop 1
	v_add_f32_dpp v48, v48, v48 quad_perm:[2,3,0,1] row_mask:0xf bank_mask:0xf
	v_bfe_u32 v60, v52, 16, 1
	v_add3_u32 v52, v52, v60, s82
	v_add_u32_e32 v60, s50, v134
	ds_write_b16_d16_hi v60, v52 offset:17408
	s_waitcnt lgkmcnt(1)
	s_nop 1
	v_add_f32_dpp v48, v48, v48 row_half_mirror row_mask:0xf bank_mask:0xf
	s_nop 1
	v_add_f32_dpp v52, v48, v48 row_mirror row_mask:0xf bank_mask:0xf
	v_bfe_u32 v56, v68, 16, 1
	v_add3_u32 v56, v68, v56, s82
	v_add_u32_e32 v60, s51, v134
	ds_write_b16_d16_hi v60, v56 offset:17408
	s_and_saveexec_b64 s[46:47], s[22:23]
	s_cbranch_execz .LBB0_1153
	s_waitcnt lgkmcnt(1)
	v_mov_b32_e32 v48, v52
	ds_add_f32 v135, v48
.LBB0_1153:
	s_or_b64 exec, exec, s[46:47]
	ds_read_b32 v48, v136
	s_waitcnt lgkmcnt(2)
	ds_read_b32 v52, v137
	ds_read_b32 v56, v138
	ds_read_b32 v60, v139
	s_waitcnt lgkmcnt(3)
	v_fma_f32 v53, v69, v48, v53
	s_waitcnt lgkmcnt(1)
	v_fmac_f32_e32 v52, v48, v56
	s_waitcnt lgkmcnt(0)
	v_max_f32_e32 v56, v60, v60
	v_max_f32_e64 v52, |v52|, v56
	v_rcp_f32_e32 v52, v52
	v_fma_f32 v56, v77, v48, v57
	v_fma_f32 v57, v65, v48, v61
	v_fma_f32 v48, v73, v48, v49
	v_mul_f32_e32 v57, v57, v52
	v_mul_f32_e32 v56, v56, v52
	v_mul_f32_e32 v60, v57, v57
	v_fmac_f32_e32 v60, v56, v56
	v_mul_f32_e32 v53, v53, v52
	v_fmac_f32_e32 v60, v53, v53
	v_mul_f32_e32 v52, v48, v52
	v_fmac_f32_e32 v60, v52, v52
	v_bfe_u32 v49, v56, 16, 1
	v_add3_u32 v49, v56, v49, s82
	v_add_u32_e32 v56, s3, v140
	ds_write_b16_d16_hi v56, v49 offset:17408
	s_waitcnt lgkmcnt(1)
	s_nop 1
	v_add_f32_dpp v48, v60, v60 quad_perm:[1,0,3,2] row_mask:0xf bank_mask:0xf
	v_bfe_u32 v56, v57, 16, 1
	v_add3_u32 v56, v57, v56, s82
	v_add_u32_e32 v57, s33, v140
	ds_write_b16_d16_hi v57, v56 offset:17408
	s_waitcnt lgkmcnt(1)
	s_nop 1
	v_add_f32_dpp v48, v48, v48 quad_perm:[2,3,0,1] row_mask:0xf bank_mask:0xf
	v_bfe_u32 v56, v53, 16, 1
	v_add3_u32 v53, v53, v56, s82
	v_add_u32_e32 v56, s50, v140
	ds_write_b16_d16_hi v56, v53 offset:17408
	s_waitcnt lgkmcnt(1)
	s_nop 1
	v_add_f32_dpp v48, v48, v48 row_half_mirror row_mask:0xf bank_mask:0xf
	s_nop 1
	v_add_f32_dpp v49, v48, v48 row_mirror row_mask:0xf bank_mask:0xf
	v_bfe_u32 v53, v52, 16, 1
	v_add3_u32 v52, v52, v53, s82
	v_add_u32_e32 v53, s51, v140
	ds_write_b16_d16_hi v53, v52 offset:17408
	s_and_saveexec_b64 s[46:47], s[22:23]
	s_cbranch_execz .LBB0_1155
	s_waitcnt lgkmcnt(1)
	v_mov_b32_e32 v48, v49
	ds_add_f32 v141, v48
; __device__ __forceinline__ unsigned f2bf(float f) { unsigned u = __builtin_bit_cast(unsigned, f); return (u + 0x7fffu + ((u >> 16) & 1u)) >> 16; }
; __device__ __forceinline__ void m3_phase(const Params& p, unsigned char* ldsg, int G) {
;     ...
;             for (int j = 0; j < 4; ++j) {
;                 const int l = 16 * lt + fq * 4 + j; const float iw = sIW[l]; const float qn = sRS[l] + iw * sQN[l];
;                 const float den = fmaxf(fabsf(qn), sEMT[l]); const float inv = __builtin_amdgcn_rcpf(den); float hs = 0.f;
; #pragma unroll
;                 for (int n = 0; n < 4; ++n) { const float v = (a1[n][j] + iw * a2[n][j]) * inv; hs += v * v; Ks[l * QP + 16 * (4 * (wave & 1) + n) + fr] = (bf16)f2bf(v); }
;                 hs += __shfl_xor(hs, 1); hs += __shfl_xor(hs, 2); hs += __shfl_xor(hs, 4); hs += __shfl_xor(hs, 8);
;                 if (fr == 0) atomicAdd(&sHS[l], hs);
.LBB0_1155:
	s_or_b64 exec, exec, s[46:47]
	ds_read_b32 v48, v142
	s_waitcnt lgkmcnt(2)
	ds_read_b32 v49, v143
	ds_read_b32 v52, v144
	ds_read_b32 v53, v145
	s_waitcnt lgkmcnt(3)
	v_fma_f32 v54, v70, v48, v54
	s_waitcnt lgkmcnt(1)
	v_fmac_f32_e32 v49, v48, v52
	s_waitcnt lgkmcnt(0)
	v_max_f32_e32 v52, v53, v53
	v_max_f32_e64 v49, |v49|, v52
	v_rcp_f32_e32 v49, v49
	v_fma_f32 v53, v66, v48, v62
	v_fma_f32 v52, v78, v48, v58
	v_fma_f32 v48, v74, v48, v50
	v_mul_f32_e32 v53, v53, v49
	v_mul_f32_e32 v52, v52, v49
	v_mul_f32_e32 v56, v53, v53
	v_fmac_f32_e32 v56, v52, v52
	v_mul_f32_e32 v54, v54, v49
	v_fmac_f32_e32 v56, v54, v54
	v_mul_f32_e32 v50, v48, v49
	v_fmac_f32_e32 v56, v50, v50
	v_bfe_u32 v49, v52, 16, 1
	v_add3_u32 v49, v52, v49, s82
	v_add_u32_e32 v52, s3, v146
	ds_write_b16_d16_hi v52, v49 offset:17408
	s_waitcnt lgkmcnt(1)
	s_nop 1
	v_add_f32_dpp v48, v56, v56 quad_perm:[1,0,3,2] row_mask:0xf bank_mask:0xf
	v_bfe_u32 v52, v53, 16, 1
	v_add3_u32 v52, v53, v52, s82
	v_add_u32_e32 v53, s33, v146
	ds_write_b16_d16_hi v53, v52 offset:17408
	s_waitcnt lgkmcnt(1)
	s_nop 1
	v_add_f32_dpp v48, v48, v48 quad_perm:[2,3,0,1] row_mask:0xf bank_mask:0xf
	v_bfe_u32 v52, v54, 16, 1
	v_add3_u32 v52, v54, v52, s82
	v_add_u32_e32 v53, s50, v146
	ds_write_b16_d16_hi v53, v52 offset:17408
	s_waitcnt lgkmcnt(1)
	s_nop 1
	v_add_f32_dpp v48, v48, v48 row_half_mirror row_mask:0xf bank_mask:0xf
	s_nop 1
	v_add_f32_dpp v49, v48, v48 row_mirror row_mask:0xf bank_mask:0xf
	v_bfe_u32 v52, v50, 16, 1
	v_add3_u32 v50, v50, v52, s82
	v_add_u32_e32 v52, s51, v146
	ds_write_b16_d16_hi v52, v50 offset:17408
	s_and_saveexec_b64 s[46:47], s[22:23]
	s_cbranch_execz .LBB0_1157
	s_waitcnt lgkmcnt(1)
	v_mov_b32_e32 v48, v49
	ds_add_f32 v147, v48
.LBB0_1157:
	s_or_b64 exec, exec, s[46:47]
	ds_read_b32 v48, v148
	s_waitcnt lgkmcnt(2)
	ds_read_b32 v49, v149
	ds_read_b32 v50, v150
	ds_read_b32 v52, v151
	s_waitcnt lgkmcnt(3)
	v_fmac_f32_e32 v63, v67, v48
	v_fmac_f32_e32 v59, v79, v48
	s_waitcnt lgkmcnt(1)
	v_fmac_f32_e32 v49, v48, v50
	s_waitcnt lgkmcnt(0)
	v_max_f32_e32 v50, v52, v52
	v_max_f32_e64 v49, |v49|, v50
	v_rcp_f32_e32 v49, v49
	v_fmac_f32_e32 v55, v71, v48
	v_fmac_f32_e32 v51, v75, v48
	v_mul_f32_e32 v52, v63, v49
	v_mul_f32_e32 v50, v59, v49
	v_mul_f32_e32 v53, v52, v52
	v_fmac_f32_e32 v53, v50, v50
	v_mul_f32_e32 v54, v55, v49
	v_fmac_f32_e32 v53, v54, v54
	v_mul_f32_e32 v51, v51, v49
	v_fmac_f32_e32 v53, v51, v51
	v_bfe_u32 v49, v50, 16, 1
	v_add3_u32 v49, v50, v49, s82
	v_add_u32_e32 v50, s3, v157
	ds_write_b16_d16_hi v50, v49 offset:17408
	s_waitcnt lgkmcnt(1)
	s_nop 1
	v_add_f32_dpp v48, v53, v53 quad_perm:[1,0,3,2] row_mask:0xf bank_mask:0xf
	v_bfe_u32 v50, v52, 16, 1
	v_add3_u32 v50, v52, v50, s82
	v_add_u32_e32 v52, s33, v157
	ds_write_b16_d16_hi v52, v50 offset:17408
	s_waitcnt lgkmcnt(1)
	s_nop 1
	v_add_f32_dpp v48, v48, v48 quad_perm:[2,3,0,1] row_mask:0xf bank_mask:0xf
	v_bfe_u32 v50, v54, 16, 1
	v_add3_u32 v50, v54, v50, s82
	v_add_u32_e32 v52, s50, v157
	ds_write_b16_d16_hi v52, v50 offset:17408
	s_waitcnt lgkmcnt(1)
	s_nop 1
	v_add_f32_dpp v48, v48, v48 row_half_mirror row_mask:0xf bank_mask:0xf
	s_nop 1
	v_add_f32_dpp v49, v48, v48 row_mirror row_mask:0xf bank_mask:0xf
	v_bfe_u32 v50, v51, 16, 1
	v_add3_u32 v50, v51, v50, s82
	v_add_u32_e32 v51, s51, v157
	ds_write_b16_d16_hi v51, v50 offset:17408
	s_and_saveexec_b64 s[46:47], s[22:23]
	s_cbranch_execz .LBB0_1118
	s_waitcnt lgkmcnt(1)
	v_mov_b32_e32 v48, v49
	ds_add_f32 v159, v48
	s_branch .LBB0_1118
